# branch-merge epilogue: gate loads and merged-output stores with the row-major lane re-map (ds_bpermute), on top of the SwiGLU/W_in epilogue store re-map
# baseline (speedup 1.0000x reference)
;     __device__ __forceinline__ void operator()(f32x4 (&acc)[2][2][4][2], const Unit& u, int wr, int wc, int fr, int fq) const {
;         const int b = u.pm / nMt, pm = u.pm - b * nMt, pn = u.pn - b * 4;
;         const int row0 = pm * BM + wr * 64 + fr, col0 = pn * BM + wc * 32 + 8 * fq;
; #pragma unroll
;         for (int ai = 0; ai < 2; ++ai) {
;             u32x4 gw[4][2], gn[4][2];
; #pragma unroll
;             for (int m = 0; m < 4; ++m)
; #pragma unroll
;                 for (int bj = 0; bj < 2; ++bj) {
;                     const size_t row = (size_t)(row0 + ai * HALF + m * 16); const int col = col0 + bj * HALF;
;                     gw[m][bj] = *(const u32x4*)(Gt + row * 3072 + b * 1024 + col);
;                     if (b < 2) gn[m][bj] = *(const u32x4*)(Gt + row * 3072 + (b + 1) * 1024 + col); else gn[m][bj] = gw[m][bj];
;                 }
.LBB0_390:
	v_readlane_b32 s42, v253, 17
	s_mov_b32 s34, s37
	v_bfe_u32 v1, v231, 2, 2
	v_lshrrev_b32_e32 v133, 4, v231
	v_lshl_add_u32 v1, v1, 2, v133
	v_mov_b32_e32 v2, s42
	v_readlane_b32 s42, v253, 18
	s_mov_b32 s35, s2
	v_and_b32_e32 v132, 3, v231
	v_mov_b32_e32 v133, s42
	s_ashr_i32 s42, s14, 31
	ds_read_b64 v[2:3], v2
	ds_read_b64 v[134:135], v133
	s_lshr_b32 s42, s42, 26
	s_add_i32 s42, s14, s42
	s_ashr_i32 s42, s42, 6
	s_lshl_b32 s43, s14, 8
	s_lshl_b32 s44, s42, 14
	s_lshl_b32 s52, s42, 10
	s_lshl_b32 s15, s15, 8
	s_sub_i32 s43, s43, s44
	s_lshl_b32 s35, s35, 6
	s_lshl_b32 s34, s34, 5
	s_sub_i32 s15, s15, s52
	s_waitcnt lgkmcnt(0)
	v_readfirstlane_b32 s51, v3
	v_readfirstlane_b32 s50, v2
	s_add_i32 s35, s35, s43
	s_add_i32 s15, s15, s34
	v_add_u32_e32 v214, s35, v1
	v_lshl_add_u32 v2, v132, 3, s15
	v_mov_b64_e32 v[132:133], s[50:51]
	s_movk_i32 s15, 0x1800
	s_ashr_i32 s53, s52, 31
	v_mad_i64_i32 v[132:133], s[34:35], v214, s15, v[132:133]
	v_lshl_add_u64 v[132:133], s[52:53], 1, v[132:133]
	v_ashrrev_i32_e32 v3, 31, v2
	v_lshl_add_u64 v[132:133], v[2:3], 1, v[132:133]
	s_cmpk_lt_i32 s14, 0x80
	s_cselect_b64 s[34:35], -1, 0
	s_cmpk_gt_i32 s14, 0x7f
	s_cselect_b64 s[54:55], -1, 0
	v_readfirstlane_b32 s49, v135
	v_readfirstlane_b32 s48, v134
	v_cndmask_b32_e64 v1, 0, 1, s[34:35]
	v_cmp_ne_u32_e64 s[44:45], 1, v1
	v_add_u32_e32 v220, 16, v214
	v_add_u32_e32 v218, 32, v214
	v_add_u32_e32 v216, 48, v214
	v_ashrrev_i32_e32 v215, 31, v214
	v_mov_b64_e32 v[156:157], s[50:51]
	s_movk_i32 s14, 0x1800
	v_mad_i64_i32 v[148:149], vcc, v220, s14, v[156:157]
	v_mad_i64_i32 v[140:141], vcc, v218, s14, v[156:157]
	v_mad_i64_i32 v[222:223], vcc, v216, s14, v[156:157]
	v_lshl_add_u64 v[148:149], s[52:53], 1, v[148:149]
	v_lshl_add_u64 v[140:141], s[52:53], 1, v[140:141]
	v_lshl_add_u64 v[222:223], s[52:53], 1, v[222:223]
	v_lshl_add_u64 v[148:149], v[2:3], 1, v[148:149]
	v_lshl_add_u64 v[140:141], v[2:3], 1, v[140:141]
	v_lshl_add_u64 v[222:223], v[2:3], 1, v[222:223]
	flat_load_dwordx4 v[192:195], v[132:133]
	flat_load_dwordx4 v[184:187], v[132:133] offset:256
	flat_load_dwordx4 v[176:179], v[148:149]
	flat_load_dwordx4 v[168:171], v[148:149] offset:256
	flat_load_dwordx4 v[160:163], v[140:141]
	flat_load_dwordx4 v[152:155], v[140:141] offset:256
	flat_load_dwordx4 v[144:147], v[222:223]
	flat_load_dwordx4 v[136:139], v[222:223] offset:256
	s_and_b64 vcc, exec, s[44:45]
	s_cbranch_vccnz .Lbr_gcopy_a
	flat_load_dwordx4 v[188:191], v[132:133] offset:2048
	flat_load_dwordx4 v[180:183], v[132:133] offset:2304
	flat_load_dwordx4 v[172:175], v[148:149] offset:2048
	flat_load_dwordx4 v[164:167], v[148:149] offset:2304
	flat_load_dwordx4 v[156:159], v[140:141] offset:2048
	flat_load_dwordx4 v[148:151], v[140:141] offset:2304
	flat_load_dwordx4 v[140:143], v[222:223] offset:2048
	flat_load_dwordx4 v[132:135], v[222:223] offset:2304
	s_waitcnt vmcnt(0) lgkmcnt(0)
	v_lshrrev_b32_e32 v222, 4, v231
	v_lshl_or_b32 v222, v231, 4, v222
	v_and_b32_e32 v222, 0x33, v222
	v_and_or_b32 v222, v231, 12, v222
	v_lshlrev_b32_e32 v222, 2, v222
	ds_bpermute_b32 v192, v222, v192
	ds_bpermute_b32 v193, v222, v193
	ds_bpermute_b32 v194, v222, v194
	ds_bpermute_b32 v195, v222, v195
	ds_bpermute_b32 v184, v222, v184
	ds_bpermute_b32 v185, v222, v185
	ds_bpermute_b32 v186, v222, v186
	ds_bpermute_b32 v187, v222, v187
	ds_bpermute_b32 v176, v222, v176
	ds_bpermute_b32 v177, v222, v177
	ds_bpermute_b32 v178, v222, v178
	ds_bpermute_b32 v179, v222, v179
	ds_bpermute_b32 v168, v222, v168
	ds_bpermute_b32 v169, v222, v169
	ds_bpermute_b32 v170, v222, v170
	ds_bpermute_b32 v171, v222, v171
	ds_bpermute_b32 v160, v222, v160
	ds_bpermute_b32 v161, v222, v161
	ds_bpermute_b32 v162, v222, v162
	ds_bpermute_b32 v163, v222, v163
	ds_bpermute_b32 v152, v222, v152
	ds_bpermute_b32 v153, v222, v153
	ds_bpermute_b32 v154, v222, v154
	ds_bpermute_b32 v155, v222, v155
	ds_bpermute_b32 v144, v222, v144
	ds_bpermute_b32 v145, v222, v145
	ds_bpermute_b32 v146, v222, v146
	ds_bpermute_b32 v147, v222, v147
	ds_bpermute_b32 v136, v222, v136
	ds_bpermute_b32 v137, v222, v137
	ds_bpermute_b32 v138, v222, v138
	ds_bpermute_b32 v139, v222, v139
	ds_bpermute_b32 v188, v222, v188
	ds_bpermute_b32 v189, v222, v189
	ds_bpermute_b32 v190, v222, v190
	ds_bpermute_b32 v191, v222, v191
	ds_bpermute_b32 v180, v222, v180
	ds_bpermute_b32 v181, v222, v181
	ds_bpermute_b32 v182, v222, v182
	ds_bpermute_b32 v183, v222, v183
	ds_bpermute_b32 v172, v222, v172
	ds_bpermute_b32 v173, v222, v173
	ds_bpermute_b32 v174, v222, v174
	ds_bpermute_b32 v175, v222, v175
	ds_bpermute_b32 v164, v222, v164
	ds_bpermute_b32 v165, v222, v165
	ds_bpermute_b32 v166, v222, v166
	ds_bpermute_b32 v167, v222, v167
	ds_bpermute_b32 v156, v222, v156
	ds_bpermute_b32 v157, v222, v157
	ds_bpermute_b32 v158, v222, v158
	ds_bpermute_b32 v159, v222, v159
	ds_bpermute_b32 v148, v222, v148
	ds_bpermute_b32 v149, v222, v149
	ds_bpermute_b32 v150, v222, v150
	ds_bpermute_b32 v151, v222, v151
	ds_bpermute_b32 v140, v222, v140
	ds_bpermute_b32 v141, v222, v141
	ds_bpermute_b32 v142, v222, v142
	ds_bpermute_b32 v143, v222, v143
	ds_bpermute_b32 v132, v222, v132
	ds_bpermute_b32 v133, v222, v133
	ds_bpermute_b32 v134, v222, v134
	ds_bpermute_b32 v135, v222, v135
	s_waitcnt lgkmcnt(0)
	s_branch .LBB0_406
; __device__ __forceinline__ unsigned cvt_pk_bf16(float lo, float hi) { unsigned r; asm volatile("v_cvt_pk_bf16_f32 %0, %1, %2" : "=v"(r) : "v"(lo), "v"(hi)); return r; }
; __device__ __forceinline__ float bflo(unsigned w) { return __uint_as_float(w << 16); }
; __device__ __forceinline__ float bfhi(unsigned w) { return __uint_as_float(w & 0xffff0000u); }
;     __device__ __forceinline__ void operator()(f32x4 (&acc)[2][2][4][2], const Unit& u, int wr, int wc, int fr, int fq) const {
;     ...
;                     if (b < 2) gn[m][bj] = *(const u32x4*)(Gt + row * 3072 + (b + 1) * 1024 + col); else gn[m][bj] = gw[m][bj];
;                 }
; #pragma unroll
;             for (int m = 0; m < 4; ++m)
; #pragma unroll
;                 for (int bj = 0; bj < 2; ++bj) {
;                     const u32x4 g = gw[m][bj], h = gn[m][bj];
;                     f32x4 g0 = {bflo(g.x), bfhi(g.x), bflo(g.y), bfhi(g.y)}, g1 = {bflo(g.z), bfhi(g.z), bflo(g.w), bfhi(g.w)};
;                     if (b < 2) {
;                         const f32x4 h0 = {bflo(h.x), bfhi(h.x), bflo(h.y), bfhi(h.y)}, h1 = {bflo(h.z), bfhi(h.z), bflo(h.w), bfhi(h.w)};
; #pragma unroll
;                         for (int j = 0; j < 4; ++j) { g0[j] = h0[j] * __builtin_amdgcn_rcpf(g0[j]); g1[j] = h1[j] * __builtin_amdgcn_rcpf(g1[j]); }
;                         acc[ai][bj][m][0] = acc[ai][bj][m][0] * g0; acc[ai][bj][m][1] = acc[ai][bj][m][1] * g1;
;                     } else {
;                         const size_t row = (size_t)(row0 + ai * HALF + m * 16); const int col = col0 + bj * HALF;
; #pragma unroll
;                         for (int j = 0; j < 4; ++j) { g0[j] = __builtin_amdgcn_rcpf(g0[j]); g1[j] = __builtin_amdgcn_rcpf(g1[j]); }
;                         const f32x4 v0 = acc[ai][bj][m][0] * g0, v1 = acc[ai][bj][m][1] * g1;
;                         u32x4 w; w.x = cvt_pk_bf16(v0[0], v0[1]); w.y = cvt_pk_bf16(v0[2], v0[3]); w.z = cvt_pk_bf16(v1[0], v1[1]); w.w = cvt_pk_bf16(v1[2], v1[3]);
;                         *(u32x4*)(Mg + row * 1024 + col) = w;
.Lbr_gcopy_a:
	s_waitcnt vmcnt(0) lgkmcnt(0)
	v_lshrrev_b32_e32 v222, 4, v231
	v_lshl_or_b32 v222, v231, 4, v222
	v_and_b32_e32 v222, 0x33, v222
	v_and_or_b32 v222, v231, 12, v222
	v_lshlrev_b32_e32 v222, 2, v222
	ds_bpermute_b32 v192, v222, v192
	ds_bpermute_b32 v193, v222, v193
	ds_bpermute_b32 v194, v222, v194
	ds_bpermute_b32 v195, v222, v195
	ds_bpermute_b32 v184, v222, v184
	ds_bpermute_b32 v185, v222, v185
	ds_bpermute_b32 v186, v222, v186
	ds_bpermute_b32 v187, v222, v187
	ds_bpermute_b32 v176, v222, v176
	ds_bpermute_b32 v177, v222, v177
	ds_bpermute_b32 v178, v222, v178
	ds_bpermute_b32 v179, v222, v179
	ds_bpermute_b32 v168, v222, v168
	ds_bpermute_b32 v169, v222, v169
	ds_bpermute_b32 v170, v222, v170
	ds_bpermute_b32 v171, v222, v171
	ds_bpermute_b32 v160, v222, v160
	ds_bpermute_b32 v161, v222, v161
	ds_bpermute_b32 v162, v222, v162
	ds_bpermute_b32 v163, v222, v163
	ds_bpermute_b32 v152, v222, v152
	ds_bpermute_b32 v153, v222, v153
	ds_bpermute_b32 v154, v222, v154
	ds_bpermute_b32 v155, v222, v155
	ds_bpermute_b32 v144, v222, v144
	ds_bpermute_b32 v145, v222, v145
	ds_bpermute_b32 v146, v222, v146
	ds_bpermute_b32 v147, v222, v147
	ds_bpermute_b32 v136, v222, v136
	ds_bpermute_b32 v137, v222, v137
	ds_bpermute_b32 v138, v222, v138
	ds_bpermute_b32 v139, v222, v139
	s_waitcnt lgkmcnt(0)
	v_mov_b64_e32 v[188:189], v[192:193]
	v_mov_b64_e32 v[190:191], v[194:195]
	v_mov_b64_e32 v[180:181], v[184:185]
	v_mov_b64_e32 v[182:183], v[186:187]
	v_mov_b64_e32 v[172:173], v[176:177]
	v_mov_b64_e32 v[174:175], v[178:179]
	v_mov_b64_e32 v[164:165], v[168:169]
	v_mov_b64_e32 v[166:167], v[170:171]
	v_mov_b64_e32 v[156:157], v[160:161]
	v_mov_b64_e32 v[158:159], v[162:163]
	v_mov_b64_e32 v[148:149], v[152:153]
	v_mov_b64_e32 v[150:151], v[154:155]
	v_mov_b64_e32 v[140:141], v[144:145]
	v_mov_b64_e32 v[142:143], v[146:147]
	v_mov_b64_e32 v[132:133], v[136:137]
	v_mov_b64_e32 v[134:135], v[138:139]
.LBB0_406:
	v_lshlrev_b64 v[248:249], 11, v[214:215]
	v_lshlrev_b32_e32 v1, 16, v192
	v_and_b32_e32 v192, 0xffff0000, v192
	v_lshlrev_b32_e32 v196, 16, v193
	v_and_b32_e32 v193, 0xffff0000, v193
	v_lshlrev_b32_e32 v197, 16, v194
	v_and_b32_e32 v194, 0xffff0000, v194
	v_lshlrev_b32_e32 v215, 16, v195
	v_and_b32_e32 v195, 0xffff0000, v195
	v_rcp_f32_e32 v226, v1
	v_rcp_f32_e32 v224, v197
	v_rcp_f32_e32 v227, v192
	v_rcp_f32_e32 v225, v194
	v_rcp_f32_e32 v222, v196
	v_rcp_f32_e32 v194, v215
	v_rcp_f32_e32 v223, v193
	v_rcp_f32_e32 v195, v195
	v_lshl_add_u64 v[192:193], s[48:49], 0, v[248:249]
	s_mov_b64 s[34:35], -1
	s_and_b64 vcc, exec, s[54:55]
	v_lshl_add_u64 v[192:193], v[2:3], 1, v[192:193]
	s_cbranch_vccz .LBB0_408
	v_pk_mul_f32 v[250:251], v[130:131], v[222:223]
	v_pk_mul_f32 v[248:249], v[128:129], v[226:227]
	v_pk_mul_f32 v[232:233], v[124:125], v[224:225]
	v_pk_mul_f32 v[196:197], v[126:127], v[194:195]
	v_cvt_pk_bf16_f32 v248, v248, v249
	v_cvt_pk_bf16_f32 v249, v250, v251
	v_cvt_pk_bf16_f32 v250, v232, v233
	v_lshlrev_b32_e32 v232, 1, v247
	v_cvt_pk_bf16_f32 v251, v196, v197
	v_lshrrev_b32_e32 v1, 4, v231
	v_lshl_or_b32 v1, v231, 4, v1
	v_and_b32_e32 v1, 0x33, v1
	v_and_or_b32 v1, v231, 12, v1
	v_lshlrev_b32_e32 v1, 2, v1
	ds_bpermute_b32 v248, v1, v248
	ds_bpermute_b32 v249, v1, v249
	ds_bpermute_b32 v250, v1, v250
	ds_bpermute_b32 v251, v1, v251
	s_waitcnt lgkmcnt(0)
	global_store_dwordx4 v[192:193], v[248:251], off
	s_mov_b64 s[34:35], 0

; __device__ __forceinline__ unsigned cvt_pk_bf16(float lo, float hi) { unsigned r; asm volatile("v_cvt_pk_bf16_f32 %0, %1, %2" : "=v"(r) : "v"(lo), "v"(hi)); return r; }
; __device__ __forceinline__ float bflo(unsigned w) { return __uint_as_float(w << 16); }
; __device__ __forceinline__ float bfhi(unsigned w) { return __uint_as_float(w & 0xffff0000u); }
;     __device__ __forceinline__ void operator()(f32x4 (&acc)[2][2][4][2], const Unit& u, int wr, int wc, int fr, int fq) const {
;     ...
;                 for (int bj = 0; bj < 2; ++bj) {
;                     const u32x4 g = gw[m][bj], h = gn[m][bj];
;                     f32x4 g0 = {bflo(g.x), bfhi(g.x), bflo(g.y), bfhi(g.y)}, g1 = {bflo(g.z), bfhi(g.z), bflo(g.w), bfhi(g.w)};
;                     if (b < 2) {
;                         const f32x4 h0 = {bflo(h.x), bfhi(h.x), bflo(h.y), bfhi(h.y)}, h1 = {bflo(h.z), bfhi(h.z), bflo(h.w), bfhi(h.w)};
; #pragma unroll
;                         for (int j = 0; j < 4; ++j) { g0[j] = h0[j] * __builtin_amdgcn_rcpf(g0[j]); g1[j] = h1[j] * __builtin_amdgcn_rcpf(g1[j]); }
;                         acc[ai][bj][m][0] = acc[ai][bj][m][0] * g0; acc[ai][bj][m][1] = acc[ai][bj][m][1] * g1;
;                     } else {
;                         const size_t row = (size_t)(row0 + ai * HALF + m * 16); const int col = col0 + bj * HALF;
; #pragma unroll
;                         for (int j = 0; j < 4; ++j) { g0[j] = __builtin_amdgcn_rcpf(g0[j]); g1[j] = __builtin_amdgcn_rcpf(g1[j]); }
;                         const f32x4 v0 = acc[ai][bj][m][0] * g0, v1 = acc[ai][bj][m][1] * g1;
;                         u32x4 w; w.x = cvt_pk_bf16(v0[0], v0[1]); w.y = cvt_pk_bf16(v0[2], v0[3]); w.z = cvt_pk_bf16(v1[0], v1[1]); w.w = cvt_pk_bf16(v1[2], v1[3]);
;                         *(u32x4*)(Mg + row * 1024 + col) = w;
.LBB0_410:
	v_lshlrev_b32_e32 v1, 16, v184
	v_and_b32_e32 v184, 0xffff0000, v184
	v_lshlrev_b32_e32 v194, 16, v185
	v_and_b32_e32 v185, 0xffff0000, v185
	v_lshlrev_b32_e32 v188, 16, v186
	v_and_b32_e32 v186, 0xffff0000, v186
	v_lshlrev_b32_e32 v195, 16, v187
	v_and_b32_e32 v196, 0xffff0000, v187
	v_cndmask_b32_e64 v187, 0, 1, s[54:55]
	v_cmp_ne_u32_e64 s[42:43], 1, v187
	v_rcp_f32_e32 v190, v1
	v_rcp_f32_e32 v188, v188
	v_rcp_f32_e32 v191, v184
	v_rcp_f32_e32 v189, v186
	v_rcp_f32_e32 v186, v194
	v_rcp_f32_e32 v184, v195
	v_rcp_f32_e32 v187, v185
	v_rcp_f32_e32 v185, v196
	s_mov_b64 s[56:57], -1
	s_andn2_b64 vcc, exec, s[54:55]
	s_cbranch_vccnz .LBB0_412
	v_pk_mul_f32 v[224:225], v[92:93], v[188:189]
	s_mov_b64 s[56:57], 0
	v_pk_mul_f32 v[194:195], v[98:99], v[186:187]
	v_pk_mul_f32 v[196:197], v[96:97], v[190:191]
	v_pk_mul_f32 v[226:227], v[94:95], v[184:185]
	v_cvt_pk_bf16_f32 v222, v196, v197
	v_cvt_pk_bf16_f32 v223, v194, v195
	v_cvt_pk_bf16_f32 v224, v224, v225
	s_nop 0
	v_cvt_pk_bf16_f32 v225, v226, v227
	v_lshrrev_b32_e32 v1, 4, v231
	v_lshl_or_b32 v1, v231, 4, v1
	v_and_b32_e32 v1, 0x33, v1
	v_and_or_b32 v1, v231, 12, v1
	v_lshlrev_b32_e32 v1, 2, v1
	ds_bpermute_b32 v222, v1, v222
	ds_bpermute_b32 v223, v1, v223
	ds_bpermute_b32 v224, v1, v224
	ds_bpermute_b32 v225, v1, v225
	s_waitcnt lgkmcnt(0)
	global_store_dwordx4 v[192:193], v[222:225], off offset:256

; __device__ __forceinline__ unsigned cvt_pk_bf16(float lo, float hi) { unsigned r; asm volatile("v_cvt_pk_bf16_f32 %0, %1, %2" : "=v"(r) : "v"(lo), "v"(hi)); return r; }
; __device__ __forceinline__ float bflo(unsigned w) { return __uint_as_float(w << 16); }
; __device__ __forceinline__ float bfhi(unsigned w) { return __uint_as_float(w & 0xffff0000u); }
;     __device__ __forceinline__ void operator()(f32x4 (&acc)[2][2][4][2], const Unit& u, int wr, int wc, int fr, int fq) const {
;     ...
;                 for (int bj = 0; bj < 2; ++bj) {
;                     const u32x4 g = gw[m][bj], h = gn[m][bj];
;                     f32x4 g0 = {bflo(g.x), bfhi(g.x), bflo(g.y), bfhi(g.y)}, g1 = {bflo(g.z), bfhi(g.z), bflo(g.w), bfhi(g.w)};
;                     if (b < 2) {
;                         const f32x4 h0 = {bflo(h.x), bfhi(h.x), bflo(h.y), bfhi(h.y)}, h1 = {bflo(h.z), bfhi(h.z), bflo(h.w), bfhi(h.w)};
; #pragma unroll
;                         for (int j = 0; j < 4; ++j) { g0[j] = h0[j] * __builtin_amdgcn_rcpf(g0[j]); g1[j] = h1[j] * __builtin_amdgcn_rcpf(g1[j]); }
;                         acc[ai][bj][m][0] = acc[ai][bj][m][0] * g0; acc[ai][bj][m][1] = acc[ai][bj][m][1] * g1;
;                     } else {
;                         const size_t row = (size_t)(row0 + ai * HALF + m * 16); const int col = col0 + bj * HALF;
; #pragma unroll
;                         for (int j = 0; j < 4; ++j) { g0[j] = __builtin_amdgcn_rcpf(g0[j]); g1[j] = __builtin_amdgcn_rcpf(g1[j]); }
;                         const f32x4 v0 = acc[ai][bj][m][0] * g0, v1 = acc[ai][bj][m][1] * g1;
;                         u32x4 w; w.x = cvt_pk_bf16(v0[0], v0[1]); w.y = cvt_pk_bf16(v0[2], v0[3]); w.z = cvt_pk_bf16(v1[0], v1[1]); w.w = cvt_pk_bf16(v1[2], v1[3]);
;                         *(u32x4*)(Mg + row * 1024 + col) = w;
.LBB0_414:
	v_lshlrev_b32_e32 v1, 16, v176
	v_and_b32_e32 v176, 0xffff0000, v176
	v_lshlrev_b32_e32 v180, 16, v177
	v_and_b32_e32 v177, 0xffff0000, v177
	v_lshlrev_b32_e32 v181, 16, v178
	v_and_b32_e32 v178, 0xffff0000, v178
	v_lshlrev_b32_e32 v188, 16, v179
	v_and_b32_e32 v179, 0xffff0000, v179
	v_ashrrev_i32_e32 v221, 31, v220
	v_rcp_f32_e32 v184, v1
	v_rcp_f32_e32 v182, v181
	v_rcp_f32_e32 v185, v176
	v_rcp_f32_e32 v183, v178
	v_rcp_f32_e32 v180, v180
	v_rcp_f32_e32 v178, v188
	v_rcp_f32_e32 v181, v177
	v_rcp_f32_e32 v179, v179
	v_lshlrev_b64 v[186:187], 11, v[220:221]
	v_lshl_add_u64 v[176:177], s[48:49], 0, v[186:187]
	s_mov_b64 s[34:35], -1
	s_and_b64 vcc, exec, s[42:43]
	v_lshl_add_u64 v[176:177], v[2:3], 1, v[176:177]
	s_cbranch_vccnz .LBB0_416
	v_pk_mul_f32 v[188:189], v[122:123], v[180:181]
	v_pk_mul_f32 v[186:187], v[120:121], v[184:185]
	s_mov_b64 s[34:35], 0
	v_pk_mul_f32 v[190:191], v[118:119], v[178:179]
	v_pk_mul_f32 v[192:193], v[116:117], v[182:183]
	v_cvt_pk_bf16_f32 v186, v186, v187
	v_cvt_pk_bf16_f32 v187, v188, v189
	s_nop 0
	v_cvt_pk_bf16_f32 v188, v192, v193
	v_cvt_pk_bf16_f32 v189, v190, v191
	v_lshrrev_b32_e32 v1, 4, v231
	v_lshl_or_b32 v1, v231, 4, v1
	v_and_b32_e32 v1, 0x33, v1
	v_and_or_b32 v1, v231, 12, v1
	v_lshlrev_b32_e32 v1, 2, v1
	ds_bpermute_b32 v186, v1, v186
	ds_bpermute_b32 v187, v1, v187
	ds_bpermute_b32 v188, v1, v188
	ds_bpermute_b32 v189, v1, v189
	s_waitcnt lgkmcnt(0)
	global_store_dwordx4 v[176:177], v[186:189], off

; __device__ __forceinline__ unsigned cvt_pk_bf16(float lo, float hi) { unsigned r; asm volatile("v_cvt_pk_bf16_f32 %0, %1, %2" : "=v"(r) : "v"(lo), "v"(hi)); return r; }
; __device__ __forceinline__ float bflo(unsigned w) { return __uint_as_float(w << 16); }
; __device__ __forceinline__ float bfhi(unsigned w) { return __uint_as_float(w & 0xffff0000u); }
;     __device__ __forceinline__ void operator()(f32x4 (&acc)[2][2][4][2], const Unit& u, int wr, int wc, int fr, int fq) const {
;     ...
;                 for (int bj = 0; bj < 2; ++bj) {
;                     const u32x4 g = gw[m][bj], h = gn[m][bj];
;                     f32x4 g0 = {bflo(g.x), bfhi(g.x), bflo(g.y), bfhi(g.y)}, g1 = {bflo(g.z), bfhi(g.z), bflo(g.w), bfhi(g.w)};
;                     if (b < 2) {
;                         const f32x4 h0 = {bflo(h.x), bfhi(h.x), bflo(h.y), bfhi(h.y)}, h1 = {bflo(h.z), bfhi(h.z), bflo(h.w), bfhi(h.w)};
; #pragma unroll
;                         for (int j = 0; j < 4; ++j) { g0[j] = h0[j] * __builtin_amdgcn_rcpf(g0[j]); g1[j] = h1[j] * __builtin_amdgcn_rcpf(g1[j]); }
;                         acc[ai][bj][m][0] = acc[ai][bj][m][0] * g0; acc[ai][bj][m][1] = acc[ai][bj][m][1] * g1;
;                     } else {
;                         const size_t row = (size_t)(row0 + ai * HALF + m * 16); const int col = col0 + bj * HALF;
; #pragma unroll
;                         for (int j = 0; j < 4; ++j) { g0[j] = __builtin_amdgcn_rcpf(g0[j]); g1[j] = __builtin_amdgcn_rcpf(g1[j]); }
;                         const f32x4 v0 = acc[ai][bj][m][0] * g0, v1 = acc[ai][bj][m][1] * g1;
;                         u32x4 w; w.x = cvt_pk_bf16(v0[0], v0[1]); w.y = cvt_pk_bf16(v0[2], v0[3]); w.z = cvt_pk_bf16(v1[0], v1[1]); w.w = cvt_pk_bf16(v1[2], v1[3]);
;                         *(u32x4*)(Mg + row * 1024 + col) = w;
.LBB0_418:
	v_lshlrev_b32_e32 v1, 16, v168
	v_and_b32_e32 v168, 0xffff0000, v168
	v_lshlrev_b32_e32 v178, 16, v169
	v_and_b32_e32 v169, 0xffff0000, v169
	v_lshlrev_b32_e32 v172, 16, v170
	v_and_b32_e32 v170, 0xffff0000, v170
	v_lshlrev_b32_e32 v179, 16, v171
	v_and_b32_e32 v180, 0xffff0000, v171
	v_rcp_f32_e32 v174, v1
	v_rcp_f32_e32 v172, v172
	v_rcp_f32_e32 v175, v168
	v_rcp_f32_e32 v173, v170
	v_rcp_f32_e32 v170, v178
	v_rcp_f32_e32 v168, v179
	v_rcp_f32_e32 v171, v169
	v_rcp_f32_e32 v169, v180
	s_and_b64 vcc, exec, s[42:43]
	s_mov_b64 s[14:15], -1
	s_cbranch_vccnz .LBB0_420
	v_pk_mul_f32 v[180:181], v[90:91], v[170:171]
	v_pk_mul_f32 v[178:179], v[88:89], v[174:175]
	s_mov_b64 s[14:15], 0
	v_pk_mul_f32 v[182:183], v[86:87], v[168:169]
	v_pk_mul_f32 v[184:185], v[84:85], v[172:173]
	v_cvt_pk_bf16_f32 v178, v178, v179
	v_cvt_pk_bf16_f32 v179, v180, v181
	s_nop 0
	v_cvt_pk_bf16_f32 v180, v184, v185
	v_cvt_pk_bf16_f32 v181, v182, v183
	v_lshrrev_b32_e32 v1, 4, v231
	v_lshl_or_b32 v1, v231, 4, v1
	v_and_b32_e32 v1, 0x33, v1
	v_and_or_b32 v1, v231, 12, v1
	v_lshlrev_b32_e32 v1, 2, v1
	ds_bpermute_b32 v178, v1, v178
	ds_bpermute_b32 v179, v1, v179
	ds_bpermute_b32 v180, v1, v180
	ds_bpermute_b32 v181, v1, v181
	s_waitcnt lgkmcnt(0)
	global_store_dwordx4 v[176:177], v[178:181], off offset:256

; __device__ __forceinline__ unsigned cvt_pk_bf16(float lo, float hi) { unsigned r; asm volatile("v_cvt_pk_bf16_f32 %0, %1, %2" : "=v"(r) : "v"(lo), "v"(hi)); return r; }
; __device__ __forceinline__ float bflo(unsigned w) { return __uint_as_float(w << 16); }
; __device__ __forceinline__ float bfhi(unsigned w) { return __uint_as_float(w & 0xffff0000u); }
;     __device__ __forceinline__ void operator()(f32x4 (&acc)[2][2][4][2], const Unit& u, int wr, int wc, int fr, int fq) const {
;     ...
;                 for (int bj = 0; bj < 2; ++bj) {
;                     const u32x4 g = gw[m][bj], h = gn[m][bj];
;                     f32x4 g0 = {bflo(g.x), bfhi(g.x), bflo(g.y), bfhi(g.y)}, g1 = {bflo(g.z), bfhi(g.z), bflo(g.w), bfhi(g.w)};
;                     if (b < 2) {
;                         const f32x4 h0 = {bflo(h.x), bfhi(h.x), bflo(h.y), bfhi(h.y)}, h1 = {bflo(h.z), bfhi(h.z), bflo(h.w), bfhi(h.w)};
; #pragma unroll
;                         for (int j = 0; j < 4; ++j) { g0[j] = h0[j] * __builtin_amdgcn_rcpf(g0[j]); g1[j] = h1[j] * __builtin_amdgcn_rcpf(g1[j]); }
;                         acc[ai][bj][m][0] = acc[ai][bj][m][0] * g0; acc[ai][bj][m][1] = acc[ai][bj][m][1] * g1;
;                     } else {
;                         const size_t row = (size_t)(row0 + ai * HALF + m * 16); const int col = col0 + bj * HALF;
; #pragma unroll
;                         for (int j = 0; j < 4; ++j) { g0[j] = __builtin_amdgcn_rcpf(g0[j]); g1[j] = __builtin_amdgcn_rcpf(g1[j]); }
;                         const f32x4 v0 = acc[ai][bj][m][0] * g0, v1 = acc[ai][bj][m][1] * g1;
;                         u32x4 w; w.x = cvt_pk_bf16(v0[0], v0[1]); w.y = cvt_pk_bf16(v0[2], v0[3]); w.z = cvt_pk_bf16(v1[0], v1[1]); w.w = cvt_pk_bf16(v1[2], v1[3]);
;                         *(u32x4*)(Mg + row * 1024 + col) = w;
.LBB0_422:
	v_lshlrev_b32_e32 v1, 16, v160
	v_and_b32_e32 v160, 0xffff0000, v160
	v_lshlrev_b32_e32 v164, 16, v161
	v_and_b32_e32 v161, 0xffff0000, v161
	v_lshlrev_b32_e32 v165, 16, v162
	v_and_b32_e32 v162, 0xffff0000, v162
	v_lshlrev_b32_e32 v172, 16, v163
	v_and_b32_e32 v163, 0xffff0000, v163
	v_ashrrev_i32_e32 v219, 31, v218
	v_rcp_f32_e32 v168, v1
	v_rcp_f32_e32 v166, v165
	v_rcp_f32_e32 v169, v160
	v_rcp_f32_e32 v167, v162
	v_rcp_f32_e32 v164, v164
	v_rcp_f32_e32 v162, v172
	v_rcp_f32_e32 v165, v161
	v_rcp_f32_e32 v163, v163
	v_lshlrev_b64 v[170:171], 11, v[218:219]
	v_lshl_add_u64 v[160:161], s[48:49], 0, v[170:171]
	s_mov_b64 s[34:35], -1
	s_and_b64 vcc, exec, s[42:43]
	v_lshl_add_u64 v[160:161], v[2:3], 1, v[160:161]
	s_cbranch_vccnz .LBB0_424
	v_pk_mul_f32 v[172:173], v[114:115], v[164:165]
	v_pk_mul_f32 v[170:171], v[112:113], v[168:169]
	s_mov_b64 s[34:35], 0
	v_pk_mul_f32 v[174:175], v[110:111], v[162:163]
	v_pk_mul_f32 v[176:177], v[108:109], v[166:167]
	v_cvt_pk_bf16_f32 v170, v170, v171
	v_cvt_pk_bf16_f32 v171, v172, v173
	s_nop 0
	v_cvt_pk_bf16_f32 v172, v176, v177
	v_cvt_pk_bf16_f32 v173, v174, v175
	v_lshrrev_b32_e32 v1, 4, v231
	v_lshl_or_b32 v1, v231, 4, v1
	v_and_b32_e32 v1, 0x33, v1
	v_and_or_b32 v1, v231, 12, v1
	v_lshlrev_b32_e32 v1, 2, v1
	ds_bpermute_b32 v170, v1, v170
	ds_bpermute_b32 v171, v1, v171
	ds_bpermute_b32 v172, v1, v172
	ds_bpermute_b32 v173, v1, v173
	s_waitcnt lgkmcnt(0)
	global_store_dwordx4 v[160:161], v[170:173], off

; __device__ __forceinline__ unsigned cvt_pk_bf16(float lo, float hi) { unsigned r; asm volatile("v_cvt_pk_bf16_f32 %0, %1, %2" : "=v"(r) : "v"(lo), "v"(hi)); return r; }
; __device__ __forceinline__ float bflo(unsigned w) { return __uint_as_float(w << 16); }
; __device__ __forceinline__ float bfhi(unsigned w) { return __uint_as_float(w & 0xffff0000u); }
;     __device__ __forceinline__ void operator()(f32x4 (&acc)[2][2][4][2], const Unit& u, int wr, int wc, int fr, int fq) const {
;     ...
;                 for (int bj = 0; bj < 2; ++bj) {
;                     const u32x4 g = gw[m][bj], h = gn[m][bj];
;                     f32x4 g0 = {bflo(g.x), bfhi(g.x), bflo(g.y), bfhi(g.y)}, g1 = {bflo(g.z), bfhi(g.z), bflo(g.w), bfhi(g.w)};
;                     if (b < 2) {
;                         const f32x4 h0 = {bflo(h.x), bfhi(h.x), bflo(h.y), bfhi(h.y)}, h1 = {bflo(h.z), bfhi(h.z), bflo(h.w), bfhi(h.w)};
; #pragma unroll
;                         for (int j = 0; j < 4; ++j) { g0[j] = h0[j] * __builtin_amdgcn_rcpf(g0[j]); g1[j] = h1[j] * __builtin_amdgcn_rcpf(g1[j]); }
;                         acc[ai][bj][m][0] = acc[ai][bj][m][0] * g0; acc[ai][bj][m][1] = acc[ai][bj][m][1] * g1;
;                     } else {
;                         const size_t row = (size_t)(row0 + ai * HALF + m * 16); const int col = col0 + bj * HALF;
; #pragma unroll
;                         for (int j = 0; j < 4; ++j) { g0[j] = __builtin_amdgcn_rcpf(g0[j]); g1[j] = __builtin_amdgcn_rcpf(g1[j]); }
;                         const f32x4 v0 = acc[ai][bj][m][0] * g0, v1 = acc[ai][bj][m][1] * g1;
;                         u32x4 w; w.x = cvt_pk_bf16(v0[0], v0[1]); w.y = cvt_pk_bf16(v0[2], v0[3]); w.z = cvt_pk_bf16(v1[0], v1[1]); w.w = cvt_pk_bf16(v1[2], v1[3]);
;                         *(u32x4*)(Mg + row * 1024 + col) = w;
.LBB0_426:
	v_lshlrev_b32_e32 v1, 16, v152
	v_and_b32_e32 v152, 0xffff0000, v152
	v_lshlrev_b32_e32 v162, 16, v153
	v_and_b32_e32 v153, 0xffff0000, v153
	v_lshlrev_b32_e32 v156, 16, v154
	v_and_b32_e32 v154, 0xffff0000, v154
	v_lshlrev_b32_e32 v163, 16, v155
	v_and_b32_e32 v164, 0xffff0000, v155
	v_rcp_f32_e32 v158, v1
	v_rcp_f32_e32 v156, v156
	v_rcp_f32_e32 v159, v152
	v_rcp_f32_e32 v157, v154
	v_rcp_f32_e32 v154, v162
	v_rcp_f32_e32 v152, v163
	v_rcp_f32_e32 v155, v153
	v_rcp_f32_e32 v153, v164
	s_and_b64 vcc, exec, s[42:43]
	s_mov_b64 s[14:15], -1
	s_cbranch_vccnz .LBB0_428
	v_pk_mul_f32 v[164:165], v[82:83], v[154:155]
	v_pk_mul_f32 v[162:163], v[80:81], v[158:159]
	s_mov_b64 s[14:15], 0
	v_pk_mul_f32 v[166:167], v[78:79], v[152:153]
	v_pk_mul_f32 v[168:169], v[76:77], v[156:157]
	v_cvt_pk_bf16_f32 v162, v162, v163
	v_cvt_pk_bf16_f32 v163, v164, v165
	s_nop 0
	v_cvt_pk_bf16_f32 v164, v168, v169
	v_cvt_pk_bf16_f32 v165, v166, v167
	v_lshrrev_b32_e32 v1, 4, v231
	v_lshl_or_b32 v1, v231, 4, v1
	v_and_b32_e32 v1, 0x33, v1
	v_and_or_b32 v1, v231, 12, v1
	v_lshlrev_b32_e32 v1, 2, v1
	ds_bpermute_b32 v162, v1, v162
	ds_bpermute_b32 v163, v1, v163
	ds_bpermute_b32 v164, v1, v164
	ds_bpermute_b32 v165, v1, v165
	s_waitcnt lgkmcnt(0)
	global_store_dwordx4 v[160:161], v[162:165], off offset:256

; __device__ __forceinline__ unsigned cvt_pk_bf16(float lo, float hi) { unsigned r; asm volatile("v_cvt_pk_bf16_f32 %0, %1, %2" : "=v"(r) : "v"(lo), "v"(hi)); return r; }
; __device__ __forceinline__ float bflo(unsigned w) { return __uint_as_float(w << 16); }
; __device__ __forceinline__ float bfhi(unsigned w) { return __uint_as_float(w & 0xffff0000u); }
;     __device__ __forceinline__ void operator()(f32x4 (&acc)[2][2][4][2], const Unit& u, int wr, int wc, int fr, int fq) const {
;     ...
;                 for (int bj = 0; bj < 2; ++bj) {
;                     const u32x4 g = gw[m][bj], h = gn[m][bj];
;                     f32x4 g0 = {bflo(g.x), bfhi(g.x), bflo(g.y), bfhi(g.y)}, g1 = {bflo(g.z), bfhi(g.z), bflo(g.w), bfhi(g.w)};
;                     if (b < 2) {
;                         const f32x4 h0 = {bflo(h.x), bfhi(h.x), bflo(h.y), bfhi(h.y)}, h1 = {bflo(h.z), bfhi(h.z), bflo(h.w), bfhi(h.w)};
; #pragma unroll
;                         for (int j = 0; j < 4; ++j) { g0[j] = h0[j] * __builtin_amdgcn_rcpf(g0[j]); g1[j] = h1[j] * __builtin_amdgcn_rcpf(g1[j]); }
;                         acc[ai][bj][m][0] = acc[ai][bj][m][0] * g0; acc[ai][bj][m][1] = acc[ai][bj][m][1] * g1;
;                     } else {
;                         const size_t row = (size_t)(row0 + ai * HALF + m * 16); const int col = col0 + bj * HALF;
; #pragma unroll
;                         for (int j = 0; j < 4; ++j) { g0[j] = __builtin_amdgcn_rcpf(g0[j]); g1[j] = __builtin_amdgcn_rcpf(g1[j]); }
;                         const f32x4 v0 = acc[ai][bj][m][0] * g0, v1 = acc[ai][bj][m][1] * g1;
;                         u32x4 w; w.x = cvt_pk_bf16(v0[0], v0[1]); w.y = cvt_pk_bf16(v0[2], v0[3]); w.z = cvt_pk_bf16(v1[0], v1[1]); w.w = cvt_pk_bf16(v1[2], v1[3]);
;                         *(u32x4*)(Mg + row * 1024 + col) = w;
.LBB0_430:
	v_lshlrev_b32_e32 v1, 16, v144
	v_and_b32_e32 v144, 0xffff0000, v144
	v_lshlrev_b32_e32 v148, 16, v145
	v_and_b32_e32 v145, 0xffff0000, v145
	v_lshlrev_b32_e32 v149, 16, v146
	v_and_b32_e32 v146, 0xffff0000, v146
	v_lshlrev_b32_e32 v156, 16, v147
	v_and_b32_e32 v147, 0xffff0000, v147
	v_ashrrev_i32_e32 v217, 31, v216
	v_rcp_f32_e32 v152, v1
	v_rcp_f32_e32 v150, v149
	v_rcp_f32_e32 v153, v144
	v_rcp_f32_e32 v151, v146
	v_rcp_f32_e32 v148, v148
	v_rcp_f32_e32 v146, v156
	v_rcp_f32_e32 v149, v145
	v_rcp_f32_e32 v147, v147
	v_lshlrev_b64 v[154:155], 11, v[216:217]
	v_lshl_add_u64 v[144:145], s[48:49], 0, v[154:155]
	s_mov_b64 s[34:35], -1
	s_and_b64 vcc, exec, s[42:43]
	v_lshl_add_u64 v[144:145], v[2:3], 1, v[144:145]
	s_cbranch_vccnz .LBB0_432
	v_pk_mul_f32 v[156:157], v[106:107], v[148:149]
	v_pk_mul_f32 v[154:155], v[104:105], v[152:153]
	s_mov_b64 s[34:35], 0
	v_pk_mul_f32 v[158:159], v[102:103], v[146:147]
	v_pk_mul_f32 v[160:161], v[100:101], v[150:151]
	v_cvt_pk_bf16_f32 v154, v154, v155
	v_cvt_pk_bf16_f32 v155, v156, v157
	s_nop 0
	v_cvt_pk_bf16_f32 v156, v160, v161
	v_cvt_pk_bf16_f32 v157, v158, v159
	v_lshrrev_b32_e32 v1, 4, v231
	v_lshl_or_b32 v1, v231, 4, v1
	v_and_b32_e32 v1, 0x33, v1
	v_and_or_b32 v1, v231, 12, v1
	v_lshlrev_b32_e32 v1, 2, v1
	ds_bpermute_b32 v154, v1, v154
	ds_bpermute_b32 v155, v1, v155
	ds_bpermute_b32 v156, v1, v156
	ds_bpermute_b32 v157, v1, v157
	s_waitcnt lgkmcnt(0)
	global_store_dwordx4 v[144:145], v[154:157], off

; __device__ __forceinline__ unsigned cvt_pk_bf16(float lo, float hi) { unsigned r; asm volatile("v_cvt_pk_bf16_f32 %0, %1, %2" : "=v"(r) : "v"(lo), "v"(hi)); return r; }
; __device__ __forceinline__ float bflo(unsigned w) { return __uint_as_float(w << 16); }
; __device__ __forceinline__ float bfhi(unsigned w) { return __uint_as_float(w & 0xffff0000u); }
;     __device__ __forceinline__ void operator()(f32x4 (&acc)[2][2][4][2], const Unit& u, int wr, int wc, int fr, int fq) const {
;     ...
;                 for (int bj = 0; bj < 2; ++bj) {
;                     const u32x4 g = gw[m][bj], h = gn[m][bj];
;                     f32x4 g0 = {bflo(g.x), bfhi(g.x), bflo(g.y), bfhi(g.y)}, g1 = {bflo(g.z), bfhi(g.z), bflo(g.w), bfhi(g.w)};
;                     if (b < 2) {
;                         const f32x4 h0 = {bflo(h.x), bfhi(h.x), bflo(h.y), bfhi(h.y)}, h1 = {bflo(h.z), bfhi(h.z), bflo(h.w), bfhi(h.w)};
; #pragma unroll
;                         for (int j = 0; j < 4; ++j) { g0[j] = h0[j] * __builtin_amdgcn_rcpf(g0[j]); g1[j] = h1[j] * __builtin_amdgcn_rcpf(g1[j]); }
;                         acc[ai][bj][m][0] = acc[ai][bj][m][0] * g0; acc[ai][bj][m][1] = acc[ai][bj][m][1] * g1;
;                     } else {
;                         const size_t row = (size_t)(row0 + ai * HALF + m * 16); const int col = col0 + bj * HALF;
; #pragma unroll
;                         for (int j = 0; j < 4; ++j) { g0[j] = __builtin_amdgcn_rcpf(g0[j]); g1[j] = __builtin_amdgcn_rcpf(g1[j]); }
;                         const f32x4 v0 = acc[ai][bj][m][0] * g0, v1 = acc[ai][bj][m][1] * g1;
;                         u32x4 w; w.x = cvt_pk_bf16(v0[0], v0[1]); w.y = cvt_pk_bf16(v0[2], v0[3]); w.z = cvt_pk_bf16(v1[0], v1[1]); w.w = cvt_pk_bf16(v1[2], v1[3]);
;                         *(u32x4*)(Mg + row * 1024 + col) = w;
.LBB0_434:
	v_lshlrev_b32_e32 v1, 16, v136
	v_and_b32_e32 v136, 0xffff0000, v136
	v_lshlrev_b32_e32 v146, 16, v137
	v_and_b32_e32 v137, 0xffff0000, v137
	v_lshlrev_b32_e32 v140, 16, v138
	v_and_b32_e32 v138, 0xffff0000, v138
	v_lshlrev_b32_e32 v147, 16, v139
	v_and_b32_e32 v148, 0xffff0000, v139
	v_rcp_f32_e32 v142, v1
	v_rcp_f32_e32 v140, v140
	v_rcp_f32_e32 v143, v136
	v_rcp_f32_e32 v141, v138
	v_rcp_f32_e32 v138, v146
	v_rcp_f32_e32 v136, v147
	v_rcp_f32_e32 v139, v137
	v_rcp_f32_e32 v137, v148
	s_and_b64 vcc, exec, s[42:43]
	s_mov_b64 s[14:15], -1
	s_cbranch_vccnz .LBB0_436
	v_pk_mul_f32 v[148:149], v[74:75], v[138:139]
	v_pk_mul_f32 v[146:147], v[72:73], v[142:143]
	s_mov_b64 s[14:15], 0
	v_pk_mul_f32 v[150:151], v[70:71], v[136:137]
	v_pk_mul_f32 v[152:153], v[68:69], v[140:141]
	v_cvt_pk_bf16_f32 v146, v146, v147
	v_cvt_pk_bf16_f32 v147, v148, v149
	s_nop 0
	v_cvt_pk_bf16_f32 v148, v152, v153
	v_cvt_pk_bf16_f32 v149, v150, v151
	v_lshrrev_b32_e32 v1, 4, v231
	v_lshl_or_b32 v1, v231, 4, v1
	v_and_b32_e32 v1, 0x33, v1
	v_and_or_b32 v1, v231, 12, v1
	v_lshlrev_b32_e32 v1, 2, v1
	ds_bpermute_b32 v146, v1, v146
	ds_bpermute_b32 v147, v1, v147
	ds_bpermute_b32 v148, v1, v148
	ds_bpermute_b32 v149, v1, v149
	s_waitcnt lgkmcnt(0)
	global_store_dwordx4 v[144:145], v[146:149], off offset:256

;     __device__ __forceinline__ void operator()(f32x4 (&acc)[2][2][4][2], const Unit& u, int wr, int wc, int fr, int fq) const {
;     ...
;         for (int ai = 0; ai < 2; ++ai) {
;             u32x4 gw[4][2], gn[4][2];
; #pragma unroll
;             for (int m = 0; m < 4; ++m)
; #pragma unroll
;                 for (int bj = 0; bj < 2; ++bj) {
;                     const size_t row = (size_t)(row0 + ai * HALF + m * 16); const int col = col0 + bj * HALF;
;                     gw[m][bj] = *(const u32x4*)(Gt + row * 3072 + b * 1024 + col);
;                     if (b < 2) gn[m][bj] = *(const u32x4*)(Gt + row * 3072 + (b + 1) * 1024 + col); else gn[m][bj] = gw[m][bj];
;                 }
.LBB0_438:
	v_add_u32_e32 v220, 0x80, v214
	s_waitcnt vmcnt(0) lgkmcnt(0)
	v_add_u32_e32 v218, 0x90, v214
	v_add_u32_e32 v216, 0xa0, v214
	v_add_u32_e32 v214, 0xb0, v214
	v_mov_b64_e32 v[156:157], s[50:51]
	s_movk_i32 s14, 0x1800
	v_mad_i64_i32 v[132:133], vcc, v220, s14, v[156:157]
	v_mad_i64_i32 v[148:149], vcc, v218, s14, v[156:157]
	v_mad_i64_i32 v[140:141], vcc, v216, s14, v[156:157]
	v_mad_i64_i32 v[222:223], vcc, v214, s14, v[156:157]
	v_lshl_add_u64 v[132:133], s[52:53], 1, v[132:133]
	v_lshl_add_u64 v[148:149], s[52:53], 1, v[148:149]
	v_lshl_add_u64 v[140:141], s[52:53], 1, v[140:141]
	v_lshl_add_u64 v[222:223], s[52:53], 1, v[222:223]
	v_lshl_add_u64 v[132:133], v[2:3], 1, v[132:133]
	v_lshl_add_u64 v[148:149], v[2:3], 1, v[148:149]
	v_lshl_add_u64 v[140:141], v[2:3], 1, v[140:141]
	v_lshl_add_u64 v[222:223], v[2:3], 1, v[222:223]
	flat_load_dwordx4 v[192:195], v[132:133]
	flat_load_dwordx4 v[184:187], v[132:133] offset:256
	flat_load_dwordx4 v[176:179], v[148:149]
	flat_load_dwordx4 v[168:171], v[148:149] offset:256
	flat_load_dwordx4 v[160:163], v[140:141]
	flat_load_dwordx4 v[152:155], v[140:141] offset:256
	flat_load_dwordx4 v[144:147], v[222:223]
	flat_load_dwordx4 v[136:139], v[222:223] offset:256
	s_and_b64 vcc, exec, s[44:45]
	s_cbranch_vccnz .Lbr_gcopy_b
	flat_load_dwordx4 v[188:191], v[132:133] offset:2048
	flat_load_dwordx4 v[180:183], v[132:133] offset:2304
	flat_load_dwordx4 v[172:175], v[148:149] offset:2048
	flat_load_dwordx4 v[164:167], v[148:149] offset:2304
	flat_load_dwordx4 v[156:159], v[140:141] offset:2048
	flat_load_dwordx4 v[148:151], v[140:141] offset:2304
	flat_load_dwordx4 v[140:143], v[222:223] offset:2048
	flat_load_dwordx4 v[132:135], v[222:223] offset:2304
	s_waitcnt vmcnt(0) lgkmcnt(0)
	v_lshrrev_b32_e32 v222, 4, v231
	v_lshl_or_b32 v222, v231, 4, v222
	v_and_b32_e32 v222, 0x33, v222
	v_and_or_b32 v222, v231, 12, v222
	v_lshlrev_b32_e32 v222, 2, v222
	ds_bpermute_b32 v192, v222, v192
	ds_bpermute_b32 v193, v222, v193
	ds_bpermute_b32 v194, v222, v194
	ds_bpermute_b32 v195, v222, v195
	ds_bpermute_b32 v184, v222, v184
	ds_bpermute_b32 v185, v222, v185
	ds_bpermute_b32 v186, v222, v186
	ds_bpermute_b32 v187, v222, v187
	ds_bpermute_b32 v176, v222, v176
	ds_bpermute_b32 v177, v222, v177
	ds_bpermute_b32 v178, v222, v178
	ds_bpermute_b32 v179, v222, v179
	ds_bpermute_b32 v168, v222, v168
	ds_bpermute_b32 v169, v222, v169
	ds_bpermute_b32 v170, v222, v170
	ds_bpermute_b32 v171, v222, v171
	ds_bpermute_b32 v160, v222, v160
	ds_bpermute_b32 v161, v222, v161
	ds_bpermute_b32 v162, v222, v162
	ds_bpermute_b32 v163, v222, v163
	ds_bpermute_b32 v152, v222, v152
	ds_bpermute_b32 v153, v222, v153
	ds_bpermute_b32 v154, v222, v154
	ds_bpermute_b32 v155, v222, v155
	ds_bpermute_b32 v144, v222, v144
	ds_bpermute_b32 v145, v222, v145
	ds_bpermute_b32 v146, v222, v146
	ds_bpermute_b32 v147, v222, v147
	ds_bpermute_b32 v136, v222, v136
	ds_bpermute_b32 v137, v222, v137
	ds_bpermute_b32 v138, v222, v138
	ds_bpermute_b32 v139, v222, v139
	ds_bpermute_b32 v188, v222, v188
	ds_bpermute_b32 v189, v222, v189
	ds_bpermute_b32 v190, v222, v190
	ds_bpermute_b32 v191, v222, v191
	ds_bpermute_b32 v180, v222, v180
	ds_bpermute_b32 v181, v222, v181
	ds_bpermute_b32 v182, v222, v182
	ds_bpermute_b32 v183, v222, v183
	ds_bpermute_b32 v172, v222, v172
	ds_bpermute_b32 v173, v222, v173
	ds_bpermute_b32 v174, v222, v174
	ds_bpermute_b32 v175, v222, v175
	ds_bpermute_b32 v164, v222, v164
	ds_bpermute_b32 v165, v222, v165
	ds_bpermute_b32 v166, v222, v166
	ds_bpermute_b32 v167, v222, v167
	ds_bpermute_b32 v156, v222, v156
	ds_bpermute_b32 v157, v222, v157
	ds_bpermute_b32 v158, v222, v158
	ds_bpermute_b32 v159, v222, v159
	ds_bpermute_b32 v148, v222, v148
	ds_bpermute_b32 v149, v222, v149
	ds_bpermute_b32 v150, v222, v150
	ds_bpermute_b32 v151, v222, v151
	ds_bpermute_b32 v140, v222, v140
	ds_bpermute_b32 v141, v222, v141
	ds_bpermute_b32 v142, v222, v142
	ds_bpermute_b32 v143, v222, v143
	ds_bpermute_b32 v132, v222, v132
	ds_bpermute_b32 v133, v222, v133
	ds_bpermute_b32 v134, v222, v134
	ds_bpermute_b32 v135, v222, v135
	s_waitcnt lgkmcnt(0)
	s_branch .LBB0_454

; __device__ __forceinline__ unsigned cvt_pk_bf16(float lo, float hi) { unsigned r; asm volatile("v_cvt_pk_bf16_f32 %0, %1, %2" : "=v"(r) : "v"(lo), "v"(hi)); return r; }
; __device__ __forceinline__ float bflo(unsigned w) { return __uint_as_float(w << 16); }
; __device__ __forceinline__ float bfhi(unsigned w) { return __uint_as_float(w & 0xffff0000u); }
;     __device__ __forceinline__ void operator()(f32x4 (&acc)[2][2][4][2], const Unit& u, int wr, int wc, int fr, int fq) const {
;     ...
;                 for (int bj = 0; bj < 2; ++bj) {
;                     const u32x4 g = gw[m][bj], h = gn[m][bj];
;                     f32x4 g0 = {bflo(g.x), bfhi(g.x), bflo(g.y), bfhi(g.y)}, g1 = {bflo(g.z), bfhi(g.z), bflo(g.w), bfhi(g.w)};
;                     if (b < 2) {
;                         const f32x4 h0 = {bflo(h.x), bfhi(h.x), bflo(h.y), bfhi(h.y)}, h1 = {bflo(h.z), bfhi(h.z), bflo(h.w), bfhi(h.w)};
; #pragma unroll
;                         for (int j = 0; j < 4; ++j) { g0[j] = h0[j] * __builtin_amdgcn_rcpf(g0[j]); g1[j] = h1[j] * __builtin_amdgcn_rcpf(g1[j]); }
;                         acc[ai][bj][m][0] = acc[ai][bj][m][0] * g0; acc[ai][bj][m][1] = acc[ai][bj][m][1] * g1;
;                     } else {
;                         const size_t row = (size_t)(row0 + ai * HALF + m * 16); const int col = col0 + bj * HALF;
; #pragma unroll
;                         for (int j = 0; j < 4; ++j) { g0[j] = __builtin_amdgcn_rcpf(g0[j]); g1[j] = __builtin_amdgcn_rcpf(g1[j]); }
;                         const f32x4 v0 = acc[ai][bj][m][0] * g0, v1 = acc[ai][bj][m][1] * g1;
;                         u32x4 w; w.x = cvt_pk_bf16(v0[0], v0[1]); w.y = cvt_pk_bf16(v0[2], v0[3]); w.z = cvt_pk_bf16(v1[0], v1[1]); w.w = cvt_pk_bf16(v1[2], v1[3]);
;                         *(u32x4*)(Mg + row * 1024 + col) = w;
.LBB0_454:
	v_ashrrev_i32_e32 v221, 31, v220
	v_lshlrev_b32_e32 v1, 16, v192
	v_and_b32_e32 v192, 0xffff0000, v192
	v_lshlrev_b32_e32 v215, 16, v193
	v_and_b32_e32 v193, 0xffff0000, v193
	v_lshlrev_b32_e32 v217, 16, v194
	v_and_b32_e32 v194, 0xffff0000, v194
	v_lshlrev_b32_e32 v219, 16, v195
	v_and_b32_e32 v195, 0xffff0000, v195
	v_lshlrev_b64 v[196:197], 11, v[220:221]
	v_rcp_f32_e32 v224, v1
	v_rcp_f32_e32 v222, v217
	v_rcp_f32_e32 v225, v192
	v_rcp_f32_e32 v223, v194
	v_rcp_f32_e32 v220, v215
	v_rcp_f32_e32 v194, v219
	v_rcp_f32_e32 v221, v193
	v_rcp_f32_e32 v195, v195
	v_lshl_add_u64 v[192:193], s[48:49], 0, v[196:197]
	s_mov_b64 s[34:35], -1
	s_and_b64 vcc, exec, s[42:43]
	v_lshl_add_u64 v[192:193], v[2:3], 1, v[192:193]
	s_cbranch_vccnz .LBB0_456
	v_pk_mul_f32 v[232:233], v[62:63], v[194:195]
	v_pk_mul_f32 v[250:251], v[60:61], v[222:223]
	v_pk_mul_f32 v[196:197], v[66:67], v[220:221]
	v_pk_mul_f32 v[226:227], v[64:65], v[224:225]
	s_mov_b64 s[34:35], 0
	v_cvt_pk_bf16_f32 v248, v226, v227
	v_cvt_pk_bf16_f32 v249, v196, v197
	v_cvt_pk_bf16_f32 v250, v250, v251
	v_cvt_pk_bf16_f32 v251, v232, v233
	v_lshlrev_b32_e32 v232, 1, v247
	v_lshrrev_b32_e32 v1, 4, v231
	v_lshl_or_b32 v1, v231, 4, v1
	v_and_b32_e32 v1, 0x33, v1
	v_and_or_b32 v1, v231, 12, v1
	v_lshlrev_b32_e32 v1, 2, v1
	ds_bpermute_b32 v248, v1, v248
	ds_bpermute_b32 v249, v1, v249
	ds_bpermute_b32 v250, v1, v250
	ds_bpermute_b32 v251, v1, v251
	s_waitcnt lgkmcnt(0)
	global_store_dwordx4 v[192:193], v[248:251], off

; __device__ __forceinline__ unsigned cvt_pk_bf16(float lo, float hi) { unsigned r; asm volatile("v_cvt_pk_bf16_f32 %0, %1, %2" : "=v"(r) : "v"(lo), "v"(hi)); return r; }
; __device__ __forceinline__ float bflo(unsigned w) { return __uint_as_float(w << 16); }
; __device__ __forceinline__ float bfhi(unsigned w) { return __uint_as_float(w & 0xffff0000u); }
;     __device__ __forceinline__ void operator()(f32x4 (&acc)[2][2][4][2], const Unit& u, int wr, int wc, int fr, int fq) const {
;     ...
;                 for (int bj = 0; bj < 2; ++bj) {
;                     const u32x4 g = gw[m][bj], h = gn[m][bj];
;                     f32x4 g0 = {bflo(g.x), bfhi(g.x), bflo(g.y), bfhi(g.y)}, g1 = {bflo(g.z), bfhi(g.z), bflo(g.w), bfhi(g.w)};
;                     if (b < 2) {
;                         const f32x4 h0 = {bflo(h.x), bfhi(h.x), bflo(h.y), bfhi(h.y)}, h1 = {bflo(h.z), bfhi(h.z), bflo(h.w), bfhi(h.w)};
; #pragma unroll
;                         for (int j = 0; j < 4; ++j) { g0[j] = h0[j] * __builtin_amdgcn_rcpf(g0[j]); g1[j] = h1[j] * __builtin_amdgcn_rcpf(g1[j]); }
;                         acc[ai][bj][m][0] = acc[ai][bj][m][0] * g0; acc[ai][bj][m][1] = acc[ai][bj][m][1] * g1;
;                     } else {
;                         const size_t row = (size_t)(row0 + ai * HALF + m * 16); const int col = col0 + bj * HALF;
; #pragma unroll
;                         for (int j = 0; j < 4; ++j) { g0[j] = __builtin_amdgcn_rcpf(g0[j]); g1[j] = __builtin_amdgcn_rcpf(g1[j]); }
;                         const f32x4 v0 = acc[ai][bj][m][0] * g0, v1 = acc[ai][bj][m][1] * g1;
;                         u32x4 w; w.x = cvt_pk_bf16(v0[0], v0[1]); w.y = cvt_pk_bf16(v0[2], v0[3]); w.z = cvt_pk_bf16(v1[0], v1[1]); w.w = cvt_pk_bf16(v1[2], v1[3]);
;                         *(u32x4*)(Mg + row * 1024 + col) = w;
.LBB0_458:
	v_lshlrev_b32_e32 v1, 16, v184
	v_and_b32_e32 v184, 0xffff0000, v184
	v_lshlrev_b32_e32 v194, 16, v185
	v_and_b32_e32 v185, 0xffff0000, v185
	v_lshlrev_b32_e32 v188, 16, v186
	v_and_b32_e32 v186, 0xffff0000, v186
	v_lshlrev_b32_e32 v195, 16, v187
	v_and_b32_e32 v196, 0xffff0000, v187
	v_rcp_f32_e32 v190, v1
	v_rcp_f32_e32 v188, v188
	v_rcp_f32_e32 v191, v184
	v_rcp_f32_e32 v189, v186
	v_rcp_f32_e32 v186, v194
	v_rcp_f32_e32 v184, v195
	v_rcp_f32_e32 v187, v185
	v_rcp_f32_e32 v185, v196
	s_and_b64 vcc, exec, s[42:43]
	s_mov_b64 s[14:15], -1
	s_cbranch_vccnz .LBB0_460
	v_pk_mul_f32 v[222:223], v[28:29], v[188:189]
	s_mov_b64 s[14:15], 0
	v_pk_mul_f32 v[194:195], v[34:35], v[186:187]
	v_pk_mul_f32 v[196:197], v[32:33], v[190:191]
	v_pk_mul_f32 v[224:225], v[30:31], v[184:185]
	v_cvt_pk_bf16_f32 v220, v196, v197
	v_cvt_pk_bf16_f32 v221, v194, v195
	v_cvt_pk_bf16_f32 v222, v222, v223
	s_nop 0
	v_cvt_pk_bf16_f32 v223, v224, v225
	v_lshrrev_b32_e32 v1, 4, v231
	v_lshl_or_b32 v1, v231, 4, v1
	v_and_b32_e32 v1, 0x33, v1
	v_and_or_b32 v1, v231, 12, v1
	v_lshlrev_b32_e32 v1, 2, v1
	ds_bpermute_b32 v220, v1, v220
	ds_bpermute_b32 v221, v1, v221
	ds_bpermute_b32 v222, v1, v222
	ds_bpermute_b32 v223, v1, v223
	s_waitcnt lgkmcnt(0)
	global_store_dwordx4 v[192:193], v[220:223], off offset:256

; __device__ __forceinline__ unsigned cvt_pk_bf16(float lo, float hi) { unsigned r; asm volatile("v_cvt_pk_bf16_f32 %0, %1, %2" : "=v"(r) : "v"(lo), "v"(hi)); return r; }
; __device__ __forceinline__ float bflo(unsigned w) { return __uint_as_float(w << 16); }
; __device__ __forceinline__ float bfhi(unsigned w) { return __uint_as_float(w & 0xffff0000u); }
;     __device__ __forceinline__ void operator()(f32x4 (&acc)[2][2][4][2], const Unit& u, int wr, int wc, int fr, int fq) const {
;     ...
;                 for (int bj = 0; bj < 2; ++bj) {
;                     const u32x4 g = gw[m][bj], h = gn[m][bj];
;                     f32x4 g0 = {bflo(g.x), bfhi(g.x), bflo(g.y), bfhi(g.y)}, g1 = {bflo(g.z), bfhi(g.z), bflo(g.w), bfhi(g.w)};
;                     if (b < 2) {
;                         const f32x4 h0 = {bflo(h.x), bfhi(h.x), bflo(h.y), bfhi(h.y)}, h1 = {bflo(h.z), bfhi(h.z), bflo(h.w), bfhi(h.w)};
; #pragma unroll
;                         for (int j = 0; j < 4; ++j) { g0[j] = h0[j] * __builtin_amdgcn_rcpf(g0[j]); g1[j] = h1[j] * __builtin_amdgcn_rcpf(g1[j]); }
;                         acc[ai][bj][m][0] = acc[ai][bj][m][0] * g0; acc[ai][bj][m][1] = acc[ai][bj][m][1] * g1;
;                     } else {
;                         const size_t row = (size_t)(row0 + ai * HALF + m * 16); const int col = col0 + bj * HALF;
; #pragma unroll
;                         for (int j = 0; j < 4; ++j) { g0[j] = __builtin_amdgcn_rcpf(g0[j]); g1[j] = __builtin_amdgcn_rcpf(g1[j]); }
;                         const f32x4 v0 = acc[ai][bj][m][0] * g0, v1 = acc[ai][bj][m][1] * g1;
;                         u32x4 w; w.x = cvt_pk_bf16(v0[0], v0[1]); w.y = cvt_pk_bf16(v0[2], v0[3]); w.z = cvt_pk_bf16(v1[0], v1[1]); w.w = cvt_pk_bf16(v1[2], v1[3]);
;                         *(u32x4*)(Mg + row * 1024 + col) = w;
.LBB0_462:
	v_lshlrev_b32_e32 v1, 16, v176
	v_and_b32_e32 v176, 0xffff0000, v176
	v_lshlrev_b32_e32 v180, 16, v177
	v_and_b32_e32 v177, 0xffff0000, v177
	v_lshlrev_b32_e32 v181, 16, v178
	v_and_b32_e32 v178, 0xffff0000, v178
	v_lshlrev_b32_e32 v188, 16, v179
	v_and_b32_e32 v179, 0xffff0000, v179
	v_ashrrev_i32_e32 v219, 31, v218
	v_rcp_f32_e32 v184, v1
	v_rcp_f32_e32 v182, v181
	v_rcp_f32_e32 v185, v176
	v_rcp_f32_e32 v183, v178
	v_rcp_f32_e32 v180, v180
	v_rcp_f32_e32 v178, v188
	v_rcp_f32_e32 v181, v177
	v_rcp_f32_e32 v179, v179
	v_lshlrev_b64 v[186:187], 11, v[218:219]
	v_lshl_add_u64 v[176:177], s[48:49], 0, v[186:187]
	s_mov_b64 s[34:35], -1
	s_and_b64 vcc, exec, s[42:43]
	v_lshl_add_u64 v[176:177], v[2:3], 1, v[176:177]
	s_cbranch_vccnz .LBB0_464
	v_pk_mul_f32 v[188:189], v[58:59], v[180:181]
	v_pk_mul_f32 v[186:187], v[56:57], v[184:185]
	s_mov_b64 s[34:35], 0
	v_pk_mul_f32 v[190:191], v[54:55], v[178:179]
	v_pk_mul_f32 v[192:193], v[52:53], v[182:183]
	v_cvt_pk_bf16_f32 v186, v186, v187
	v_cvt_pk_bf16_f32 v187, v188, v189
	s_nop 0
	v_cvt_pk_bf16_f32 v188, v192, v193
	v_cvt_pk_bf16_f32 v189, v190, v191
	v_lshrrev_b32_e32 v1, 4, v231
	v_lshl_or_b32 v1, v231, 4, v1
	v_and_b32_e32 v1, 0x33, v1
	v_and_or_b32 v1, v231, 12, v1
	v_lshlrev_b32_e32 v1, 2, v1
	ds_bpermute_b32 v186, v1, v186
	ds_bpermute_b32 v187, v1, v187
	ds_bpermute_b32 v188, v1, v188
	ds_bpermute_b32 v189, v1, v189
	s_waitcnt lgkmcnt(0)
	global_store_dwordx4 v[176:177], v[186:189], off

; __device__ __forceinline__ unsigned cvt_pk_bf16(float lo, float hi) { unsigned r; asm volatile("v_cvt_pk_bf16_f32 %0, %1, %2" : "=v"(r) : "v"(lo), "v"(hi)); return r; }
; __device__ __forceinline__ float bflo(unsigned w) { return __uint_as_float(w << 16); }
; __device__ __forceinline__ float bfhi(unsigned w) { return __uint_as_float(w & 0xffff0000u); }
;     __device__ __forceinline__ void operator()(f32x4 (&acc)[2][2][4][2], const Unit& u, int wr, int wc, int fr, int fq) const {
;     ...
;                 for (int bj = 0; bj < 2; ++bj) {
;                     const u32x4 g = gw[m][bj], h = gn[m][bj];
;                     f32x4 g0 = {bflo(g.x), bfhi(g.x), bflo(g.y), bfhi(g.y)}, g1 = {bflo(g.z), bfhi(g.z), bflo(g.w), bfhi(g.w)};
;                     if (b < 2) {
;                         const f32x4 h0 = {bflo(h.x), bfhi(h.x), bflo(h.y), bfhi(h.y)}, h1 = {bflo(h.z), bfhi(h.z), bflo(h.w), bfhi(h.w)};
; #pragma unroll
;                         for (int j = 0; j < 4; ++j) { g0[j] = h0[j] * __builtin_amdgcn_rcpf(g0[j]); g1[j] = h1[j] * __builtin_amdgcn_rcpf(g1[j]); }
;                         acc[ai][bj][m][0] = acc[ai][bj][m][0] * g0; acc[ai][bj][m][1] = acc[ai][bj][m][1] * g1;
;                     } else {
;                         const size_t row = (size_t)(row0 + ai * HALF + m * 16); const int col = col0 + bj * HALF;
; #pragma unroll
;                         for (int j = 0; j < 4; ++j) { g0[j] = __builtin_amdgcn_rcpf(g0[j]); g1[j] = __builtin_amdgcn_rcpf(g1[j]); }
;                         const f32x4 v0 = acc[ai][bj][m][0] * g0, v1 = acc[ai][bj][m][1] * g1;
;                         u32x4 w; w.x = cvt_pk_bf16(v0[0], v0[1]); w.y = cvt_pk_bf16(v0[2], v0[3]); w.z = cvt_pk_bf16(v1[0], v1[1]); w.w = cvt_pk_bf16(v1[2], v1[3]);
;                         *(u32x4*)(Mg + row * 1024 + col) = w;
.LBB0_466:
	v_lshlrev_b32_e32 v1, 16, v168
	v_and_b32_e32 v168, 0xffff0000, v168
	v_lshlrev_b32_e32 v178, 16, v169
	v_and_b32_e32 v169, 0xffff0000, v169
	v_lshlrev_b32_e32 v172, 16, v170
	v_and_b32_e32 v170, 0xffff0000, v170
	v_lshlrev_b32_e32 v179, 16, v171
	v_and_b32_e32 v180, 0xffff0000, v171
	v_rcp_f32_e32 v174, v1
	v_rcp_f32_e32 v172, v172
	v_rcp_f32_e32 v175, v168
	v_rcp_f32_e32 v173, v170
	v_rcp_f32_e32 v170, v178
	v_rcp_f32_e32 v168, v179
	v_rcp_f32_e32 v171, v169
	v_rcp_f32_e32 v169, v180
	s_and_b64 vcc, exec, s[42:43]
	s_mov_b64 s[14:15], -1
	s_cbranch_vccnz .LBB0_468
	v_pk_mul_f32 v[180:181], v[26:27], v[170:171]
	v_pk_mul_f32 v[178:179], v[24:25], v[174:175]
	s_mov_b64 s[14:15], 0
	v_pk_mul_f32 v[182:183], v[22:23], v[168:169]
	v_pk_mul_f32 v[184:185], v[20:21], v[172:173]
	v_cvt_pk_bf16_f32 v178, v178, v179
	v_cvt_pk_bf16_f32 v179, v180, v181
	s_nop 0
	v_cvt_pk_bf16_f32 v180, v184, v185
	v_cvt_pk_bf16_f32 v181, v182, v183
	v_lshrrev_b32_e32 v1, 4, v231
	v_lshl_or_b32 v1, v231, 4, v1
	v_and_b32_e32 v1, 0x33, v1
	v_and_or_b32 v1, v231, 12, v1
	v_lshlrev_b32_e32 v1, 2, v1
	ds_bpermute_b32 v178, v1, v178
	ds_bpermute_b32 v179, v1, v179
	ds_bpermute_b32 v180, v1, v180
	ds_bpermute_b32 v181, v1, v181
	s_waitcnt lgkmcnt(0)
	global_store_dwordx4 v[176:177], v[178:181], off offset:256

; __device__ __forceinline__ unsigned cvt_pk_bf16(float lo, float hi) { unsigned r; asm volatile("v_cvt_pk_bf16_f32 %0, %1, %2" : "=v"(r) : "v"(lo), "v"(hi)); return r; }
; __device__ __forceinline__ float bflo(unsigned w) { return __uint_as_float(w << 16); }
; __device__ __forceinline__ float bfhi(unsigned w) { return __uint_as_float(w & 0xffff0000u); }
;     __device__ __forceinline__ void operator()(f32x4 (&acc)[2][2][4][2], const Unit& u, int wr, int wc, int fr, int fq) const {
;     ...
;                 for (int bj = 0; bj < 2; ++bj) {
;                     const u32x4 g = gw[m][bj], h = gn[m][bj];
;                     f32x4 g0 = {bflo(g.x), bfhi(g.x), bflo(g.y), bfhi(g.y)}, g1 = {bflo(g.z), bfhi(g.z), bflo(g.w), bfhi(g.w)};
;                     if (b < 2) {
;                         const f32x4 h0 = {bflo(h.x), bfhi(h.x), bflo(h.y), bfhi(h.y)}, h1 = {bflo(h.z), bfhi(h.z), bflo(h.w), bfhi(h.w)};
; #pragma unroll
;                         for (int j = 0; j < 4; ++j) { g0[j] = h0[j] * __builtin_amdgcn_rcpf(g0[j]); g1[j] = h1[j] * __builtin_amdgcn_rcpf(g1[j]); }
;                         acc[ai][bj][m][0] = acc[ai][bj][m][0] * g0; acc[ai][bj][m][1] = acc[ai][bj][m][1] * g1;
;                     } else {
;                         const size_t row = (size_t)(row0 + ai * HALF + m * 16); const int col = col0 + bj * HALF;
; #pragma unroll
;                         for (int j = 0; j < 4; ++j) { g0[j] = __builtin_amdgcn_rcpf(g0[j]); g1[j] = __builtin_amdgcn_rcpf(g1[j]); }
;                         const f32x4 v0 = acc[ai][bj][m][0] * g0, v1 = acc[ai][bj][m][1] * g1;
;                         u32x4 w; w.x = cvt_pk_bf16(v0[0], v0[1]); w.y = cvt_pk_bf16(v0[2], v0[3]); w.z = cvt_pk_bf16(v1[0], v1[1]); w.w = cvt_pk_bf16(v1[2], v1[3]);
;                         *(u32x4*)(Mg + row * 1024 + col) = w;
.LBB0_470:
	v_lshlrev_b32_e32 v1, 16, v160
	v_and_b32_e32 v160, 0xffff0000, v160
	v_lshlrev_b32_e32 v164, 16, v161
	v_and_b32_e32 v161, 0xffff0000, v161
	v_lshlrev_b32_e32 v165, 16, v162
	v_and_b32_e32 v162, 0xffff0000, v162
	v_lshlrev_b32_e32 v172, 16, v163
	v_and_b32_e32 v163, 0xffff0000, v163
	v_ashrrev_i32_e32 v217, 31, v216
	v_rcp_f32_e32 v168, v1
	v_rcp_f32_e32 v166, v165
	v_rcp_f32_e32 v169, v160
	v_rcp_f32_e32 v167, v162
	v_rcp_f32_e32 v164, v164
	v_rcp_f32_e32 v162, v172
	v_rcp_f32_e32 v165, v161
	v_rcp_f32_e32 v163, v163
	v_lshlrev_b64 v[170:171], 11, v[216:217]
	v_lshl_add_u64 v[160:161], s[48:49], 0, v[170:171]
	s_mov_b64 s[34:35], -1
	s_and_b64 vcc, exec, s[42:43]
	v_lshl_add_u64 v[160:161], v[2:3], 1, v[160:161]
	s_cbranch_vccnz .LBB0_472
	v_pk_mul_f32 v[172:173], v[50:51], v[164:165]
	v_pk_mul_f32 v[170:171], v[48:49], v[168:169]
	s_mov_b64 s[34:35], 0
	v_pk_mul_f32 v[174:175], v[46:47], v[162:163]
	v_pk_mul_f32 v[176:177], v[44:45], v[166:167]
	v_cvt_pk_bf16_f32 v170, v170, v171
	v_cvt_pk_bf16_f32 v171, v172, v173
	s_nop 0
	v_cvt_pk_bf16_f32 v172, v176, v177
	v_cvt_pk_bf16_f32 v173, v174, v175
	v_lshrrev_b32_e32 v1, 4, v231
	v_lshl_or_b32 v1, v231, 4, v1
	v_and_b32_e32 v1, 0x33, v1
	v_and_or_b32 v1, v231, 12, v1
	v_lshlrev_b32_e32 v1, 2, v1
	ds_bpermute_b32 v170, v1, v170
	ds_bpermute_b32 v171, v1, v171
	ds_bpermute_b32 v172, v1, v172
	ds_bpermute_b32 v173, v1, v173
	s_waitcnt lgkmcnt(0)
	global_store_dwordx4 v[160:161], v[170:173], off

; __device__ __forceinline__ unsigned cvt_pk_bf16(float lo, float hi) { unsigned r; asm volatile("v_cvt_pk_bf16_f32 %0, %1, %2" : "=v"(r) : "v"(lo), "v"(hi)); return r; }
; __device__ __forceinline__ float bflo(unsigned w) { return __uint_as_float(w << 16); }
; __device__ __forceinline__ float bfhi(unsigned w) { return __uint_as_float(w & 0xffff0000u); }
;     __device__ __forceinline__ void operator()(f32x4 (&acc)[2][2][4][2], const Unit& u, int wr, int wc, int fr, int fq) const {
;     ...
;                 for (int bj = 0; bj < 2; ++bj) {
;                     const u32x4 g = gw[m][bj], h = gn[m][bj];
;                     f32x4 g0 = {bflo(g.x), bfhi(g.x), bflo(g.y), bfhi(g.y)}, g1 = {bflo(g.z), bfhi(g.z), bflo(g.w), bfhi(g.w)};
;                     if (b < 2) {
;                         const f32x4 h0 = {bflo(h.x), bfhi(h.x), bflo(h.y), bfhi(h.y)}, h1 = {bflo(h.z), bfhi(h.z), bflo(h.w), bfhi(h.w)};
; #pragma unroll
;                         for (int j = 0; j < 4; ++j) { g0[j] = h0[j] * __builtin_amdgcn_rcpf(g0[j]); g1[j] = h1[j] * __builtin_amdgcn_rcpf(g1[j]); }
;                         acc[ai][bj][m][0] = acc[ai][bj][m][0] * g0; acc[ai][bj][m][1] = acc[ai][bj][m][1] * g1;
;                     } else {
;                         const size_t row = (size_t)(row0 + ai * HALF + m * 16); const int col = col0 + bj * HALF;
; #pragma unroll
;                         for (int j = 0; j < 4; ++j) { g0[j] = __builtin_amdgcn_rcpf(g0[j]); g1[j] = __builtin_amdgcn_rcpf(g1[j]); }
;                         const f32x4 v0 = acc[ai][bj][m][0] * g0, v1 = acc[ai][bj][m][1] * g1;
;                         u32x4 w; w.x = cvt_pk_bf16(v0[0], v0[1]); w.y = cvt_pk_bf16(v0[2], v0[3]); w.z = cvt_pk_bf16(v1[0], v1[1]); w.w = cvt_pk_bf16(v1[2], v1[3]);
;                         *(u32x4*)(Mg + row * 1024 + col) = w;
.LBB0_474:
	v_lshlrev_b32_e32 v1, 16, v152
	v_and_b32_e32 v152, 0xffff0000, v152
	v_lshlrev_b32_e32 v162, 16, v153
	v_and_b32_e32 v153, 0xffff0000, v153
	v_lshlrev_b32_e32 v156, 16, v154
	v_and_b32_e32 v154, 0xffff0000, v154
	v_lshlrev_b32_e32 v163, 16, v155
	v_and_b32_e32 v164, 0xffff0000, v155
	v_rcp_f32_e32 v158, v1
	v_rcp_f32_e32 v156, v156
	v_rcp_f32_e32 v159, v152
	v_rcp_f32_e32 v157, v154
	v_rcp_f32_e32 v154, v162
	v_rcp_f32_e32 v152, v163
	v_rcp_f32_e32 v155, v153
	v_rcp_f32_e32 v153, v164
	s_and_b64 vcc, exec, s[42:43]
	s_mov_b64 s[14:15], -1
	s_cbranch_vccnz .LBB0_476
	v_pk_mul_f32 v[164:165], v[18:19], v[154:155]
	v_pk_mul_f32 v[162:163], v[16:17], v[158:159]
	s_mov_b64 s[14:15], 0
	v_pk_mul_f32 v[166:167], v[14:15], v[152:153]
	v_pk_mul_f32 v[168:169], v[12:13], v[156:157]
	v_cvt_pk_bf16_f32 v162, v162, v163
	v_cvt_pk_bf16_f32 v163, v164, v165
	s_nop 0
	v_cvt_pk_bf16_f32 v164, v168, v169
	v_cvt_pk_bf16_f32 v165, v166, v167
	v_lshrrev_b32_e32 v1, 4, v231
	v_lshl_or_b32 v1, v231, 4, v1
	v_and_b32_e32 v1, 0x33, v1
	v_and_or_b32 v1, v231, 12, v1
	v_lshlrev_b32_e32 v1, 2, v1
	ds_bpermute_b32 v162, v1, v162
	ds_bpermute_b32 v163, v1, v163
	ds_bpermute_b32 v164, v1, v164
	ds_bpermute_b32 v165, v1, v165
	s_waitcnt lgkmcnt(0)
	global_store_dwordx4 v[160:161], v[162:165], off offset:256

; __device__ __forceinline__ unsigned cvt_pk_bf16(float lo, float hi) { unsigned r; asm volatile("v_cvt_pk_bf16_f32 %0, %1, %2" : "=v"(r) : "v"(lo), "v"(hi)); return r; }
; __device__ __forceinline__ float bflo(unsigned w) { return __uint_as_float(w << 16); }
; __device__ __forceinline__ float bfhi(unsigned w) { return __uint_as_float(w & 0xffff0000u); }
;     __device__ __forceinline__ void operator()(f32x4 (&acc)[2][2][4][2], const Unit& u, int wr, int wc, int fr, int fq) const {
;     ...
;                 for (int bj = 0; bj < 2; ++bj) {
;                     const u32x4 g = gw[m][bj], h = gn[m][bj];
;                     f32x4 g0 = {bflo(g.x), bfhi(g.x), bflo(g.y), bfhi(g.y)}, g1 = {bflo(g.z), bfhi(g.z), bflo(g.w), bfhi(g.w)};
;                     if (b < 2) {
;                         const f32x4 h0 = {bflo(h.x), bfhi(h.x), bflo(h.y), bfhi(h.y)}, h1 = {bflo(h.z), bfhi(h.z), bflo(h.w), bfhi(h.w)};
; #pragma unroll
;                         for (int j = 0; j < 4; ++j) { g0[j] = h0[j] * __builtin_amdgcn_rcpf(g0[j]); g1[j] = h1[j] * __builtin_amdgcn_rcpf(g1[j]); }
;                         acc[ai][bj][m][0] = acc[ai][bj][m][0] * g0; acc[ai][bj][m][1] = acc[ai][bj][m][1] * g1;
;                     } else {
;                         const size_t row = (size_t)(row0 + ai * HALF + m * 16); const int col = col0 + bj * HALF;
; #pragma unroll
;                         for (int j = 0; j < 4; ++j) { g0[j] = __builtin_amdgcn_rcpf(g0[j]); g1[j] = __builtin_amdgcn_rcpf(g1[j]); }
;                         const f32x4 v0 = acc[ai][bj][m][0] * g0, v1 = acc[ai][bj][m][1] * g1;
;                         u32x4 w; w.x = cvt_pk_bf16(v0[0], v0[1]); w.y = cvt_pk_bf16(v0[2], v0[3]); w.z = cvt_pk_bf16(v1[0], v1[1]); w.w = cvt_pk_bf16(v1[2], v1[3]);
;                         *(u32x4*)(Mg + row * 1024 + col) = w;
.LBB0_478:
	v_lshlrev_b32_e32 v1, 16, v144
	v_and_b32_e32 v144, 0xffff0000, v144
	v_lshlrev_b32_e32 v154, 16, v145
	v_and_b32_e32 v145, 0xffff0000, v145
	v_lshlrev_b32_e32 v148, 16, v146
	v_and_b32_e32 v146, 0xffff0000, v146
	v_lshlrev_b32_e32 v155, 16, v147
	v_and_b32_e32 v156, 0xffff0000, v147
	v_ashrrev_i32_e32 v215, 31, v214
	v_rcp_f32_e32 v150, v1
	v_rcp_f32_e32 v148, v148
	v_rcp_f32_e32 v151, v144
	v_rcp_f32_e32 v149, v146
	v_rcp_f32_e32 v146, v154
	v_rcp_f32_e32 v144, v155
	v_rcp_f32_e32 v147, v145
	v_rcp_f32_e32 v145, v156
	v_lshlrev_b64 v[152:153], 11, v[214:215]
	v_lshl_add_u64 v[152:153], s[48:49], 0, v[152:153]
	s_mov_b64 s[34:35], -1
	s_and_b64 vcc, exec, s[42:43]
	v_lshl_add_u64 v[2:3], v[2:3], 1, v[152:153]
	s_cbranch_vccnz .LBB0_480
	v_pk_mul_f32 v[154:155], v[42:43], v[146:147]
	v_pk_mul_f32 v[152:153], v[40:41], v[150:151]
	s_mov_b64 s[34:35], 0
	v_pk_mul_f32 v[156:157], v[38:39], v[144:145]
	v_pk_mul_f32 v[158:159], v[36:37], v[148:149]
	v_cvt_pk_bf16_f32 v152, v152, v153
	v_cvt_pk_bf16_f32 v153, v154, v155
	s_nop 0
	v_cvt_pk_bf16_f32 v154, v158, v159
	v_cvt_pk_bf16_f32 v155, v156, v157
	v_lshrrev_b32_e32 v1, 4, v231
	v_lshl_or_b32 v1, v231, 4, v1
	v_and_b32_e32 v1, 0x33, v1
	v_and_or_b32 v1, v231, 12, v1
	v_lshlrev_b32_e32 v1, 2, v1
	ds_bpermute_b32 v152, v1, v152
	ds_bpermute_b32 v153, v1, v153
	ds_bpermute_b32 v154, v1, v154
	ds_bpermute_b32 v155, v1, v155
	s_waitcnt lgkmcnt(0)
	global_store_dwordx4 v[2:3], v[152:155], off

; __device__ __forceinline__ unsigned cvt_pk_bf16(float lo, float hi) { unsigned r; asm volatile("v_cvt_pk_bf16_f32 %0, %1, %2" : "=v"(r) : "v"(lo), "v"(hi)); return r; }
; __device__ __forceinline__ float bflo(unsigned w) { return __uint_as_float(w << 16); }
; __device__ __forceinline__ float bfhi(unsigned w) { return __uint_as_float(w & 0xffff0000u); }
;     __device__ __forceinline__ void operator()(f32x4 (&acc)[2][2][4][2], const Unit& u, int wr, int wc, int fr, int fq) const {
;     ...
;                 for (int bj = 0; bj < 2; ++bj) {
;                     const u32x4 g = gw[m][bj], h = gn[m][bj];
;                     f32x4 g0 = {bflo(g.x), bfhi(g.x), bflo(g.y), bfhi(g.y)}, g1 = {bflo(g.z), bfhi(g.z), bflo(g.w), bfhi(g.w)};
;                     if (b < 2) {
;                         const f32x4 h0 = {bflo(h.x), bfhi(h.x), bflo(h.y), bfhi(h.y)}, h1 = {bflo(h.z), bfhi(h.z), bflo(h.w), bfhi(h.w)};
; #pragma unroll
;                         for (int j = 0; j < 4; ++j) { g0[j] = h0[j] * __builtin_amdgcn_rcpf(g0[j]); g1[j] = h1[j] * __builtin_amdgcn_rcpf(g1[j]); }
;                         acc[ai][bj][m][0] = acc[ai][bj][m][0] * g0; acc[ai][bj][m][1] = acc[ai][bj][m][1] * g1;
;                     } else {
;                         const size_t row = (size_t)(row0 + ai * HALF + m * 16); const int col = col0 + bj * HALF;
; #pragma unroll
;                         for (int j = 0; j < 4; ++j) { g0[j] = __builtin_amdgcn_rcpf(g0[j]); g1[j] = __builtin_amdgcn_rcpf(g1[j]); }
;                         const f32x4 v0 = acc[ai][bj][m][0] * g0, v1 = acc[ai][bj][m][1] * g1;
;                         u32x4 w; w.x = cvt_pk_bf16(v0[0], v0[1]); w.y = cvt_pk_bf16(v0[2], v0[3]); w.z = cvt_pk_bf16(v1[0], v1[1]); w.w = cvt_pk_bf16(v1[2], v1[3]);
;                         *(u32x4*)(Mg + row * 1024 + col) = w;
.LBB0_482:
	v_lshlrev_b32_e32 v1, 16, v136
	v_and_b32_e32 v136, 0xffff0000, v136
	v_lshlrev_b32_e32 v144, 16, v137
	v_and_b32_e32 v137, 0xffff0000, v137
	v_lshlrev_b32_e32 v140, 16, v138
	v_and_b32_e32 v138, 0xffff0000, v138
	v_lshlrev_b32_e32 v145, 16, v139
	v_and_b32_e32 v146, 0xffff0000, v139
	v_rcp_f32_e32 v142, v1
	v_rcp_f32_e32 v140, v140
	v_rcp_f32_e32 v143, v136
	v_rcp_f32_e32 v141, v138
	v_rcp_f32_e32 v138, v144
	v_rcp_f32_e32 v136, v145
	v_rcp_f32_e32 v139, v137
	v_rcp_f32_e32 v137, v146
	s_and_b64 vcc, exec, s[42:43]
	s_mov_b64 s[14:15], -1
	s_cbranch_vccnz .LBB0_484
	v_pk_mul_f32 v[146:147], v[10:11], v[138:139]
	v_pk_mul_f32 v[144:145], v[8:9], v[142:143]
	s_mov_b64 s[14:15], 0
	v_pk_mul_f32 v[148:149], v[6:7], v[136:137]
	v_pk_mul_f32 v[150:151], v[4:5], v[140:141]
	v_cvt_pk_bf16_f32 v144, v144, v145
	v_cvt_pk_bf16_f32 v145, v146, v147
	s_nop 0
	v_cvt_pk_bf16_f32 v146, v150, v151
	v_cvt_pk_bf16_f32 v147, v148, v149
	v_lshrrev_b32_e32 v1, 4, v231
	v_lshl_or_b32 v1, v231, 4, v1
	v_and_b32_e32 v1, 0x33, v1
	v_and_or_b32 v1, v231, 12, v1
	v_lshlrev_b32_e32 v1, 2, v1
	ds_bpermute_b32 v144, v1, v144
	ds_bpermute_b32 v145, v1, v145
	ds_bpermute_b32 v146, v1, v146
	ds_bpermute_b32 v147, v1, v147
	s_waitcnt lgkmcnt(0)
	global_store_dwordx4 v[2:3], v[144:147], off offset:256
